# waves 0-3: P.V section starts at priority 0 and rises to 1 after 8 MFMAs (rest as previous version)
# baseline (speedup 1.0000x reference)
; #define SBAR() __builtin_amdgcn_sched_barrier(0)
; #define PV_LOAD(S, DD) do { S[0] = tr_read<v_off8(DD, 0, 0)>(vb); S[1] = tr_read<v_off8(DD, 0, 1)>(vb); S[2] = tr_read<v_off8(DD, 1, 0)>(vb); S[3] = tr_read<v_off8(DD, 1, 1)>(vb); \
;     S[4] = tr_read<v_off8(DD, 2, 0)>(vb); S[5] = tr_read<v_off8(DD, 2, 1)>(vb); S[6] = tr_read<v_off8(DD, 3, 0)>(vb); S[7] = tr_read<v_off8(DD, 3, 1)>(vb); } while (0)
; #define PV_MMA(OD, S) do { OD = __builtin_amdgcn_mfma_f32_32x32x16_bf16(pa0, PV_PK(S[0], S[1]), OD, 0, 0, 0); OD = __builtin_amdgcn_mfma_f32_32x32x16_bf16(pa1, PV_PK(S[2], S[3]), OD, 0, 0, 0); \
;     OD = __builtin_amdgcn_mfma_f32_32x32x16_bf16(pa2, PV_PK(S[4], S[5]), OD, 0, 0, 0); OD = __builtin_amdgcn_mfma_f32_32x32x16_bf16(pa3, PV_PK(S[6], S[7]), OD, 0, 0, 0); } while (0)
; #define PV_W8() do { asm volatile("s_waitcnt lgkmcnt(8)" ::: "memory"); SBAR(); } while (0)
; __device__ __forceinline__ void finishSM(f32x16& p0, f32x16& p1, float alpha, float& l_reg, bf16x8& pa0, bf16x8& pa1, bf16x8& pa2, bf16x8& pa3) {
;     ...
;   for (int r = 0; r < 16; ++r) p1[r] = __builtin_amdgcn_exp2f(p1[r]);
;   float ps = 0;
; #pragma unroll
;   for (int r = 0; r < 16; ++r) ps += p0[r];
; #pragma unroll
;   for (int r = 0; r < 16; ++r) ps += p1[r];
;   { auto rr = __builtin_amdgcn_permlane32_swap(__float_as_uint(ps), __float_as_uint(ps), false, false);
;     ps = __uint_as_float(rr[0]) + __uint_as_float(rr[1]); }
;   l_reg = l_reg * alpha + ps;
;     ...
;   PK4(p0, 0, pa0); PK4(p0, 8, pa1); PK4(p1, 0, pa2); PK4(p1, 8, pa3);
; __device__ __forceinline__ void pv8(f32x16* o, int vb, bf16x8 pa0, bf16x8 pa1, bf16x8 pa2, bf16x8 pa3) {
;   s16x4 A[8], B[8];
;   PV_LOAD(A, 0);
;   PV_LOAD(B, 1); PV_W8(); PV_MMA(o[0], A); SBAR();
;   PV_LOAD(A, 2); PV_W8(); PV_MMA(o[1], B); SBAR();
.LdA_5:
	v_add_f32_e32 v128, v202, v128
	v_exp_f32_e32 v207, v140
	v_add_f32_e32 v128, v203, v128
	v_exp_f32_e32 v208, v141
	v_add_f32_e32 v128, v204, v128
	v_exp_f32_e32 v209, v142
	v_add_f32_e32 v128, v205, v128
	v_exp_f32_e32 v194, v194
	v_add_f32_e32 v128, v206, v128
	v_add_f32_e32 v128, v207, v128
	v_add_f32_e32 v128, v208, v128
	v_add_f32_e32 v128, v209, v128
	v_add_f32_e32 v128, v194, v128
	v_mov_b32_e32 v129, v128
	s_nop 1
	v_permlane32_swap_b32_e32 v128, v129
	v_add_f32_e32 v144, v128, v129
	v_fmac_f32_e32 v144, v228, v160
	v_cvt_pk_bf16_f32 v128, v143, v145
	v_cvt_pk_bf16_f32 v129, v146, v147
	v_cvt_pk_bf16_f32 v130, v148, v149
	v_cvt_pk_bf16_f32 v131, v150, v151
	v_cvt_pk_bf16_f32 v132, v152, v153
	v_cvt_pk_bf16_f32 v133, v154, v155
	v_cvt_pk_bf16_f32 v134, v156, v157
	v_cvt_pk_bf16_f32 v135, v158, v159
	v_cvt_pk_bf16_f32 v136, v195, v196
	v_cvt_pk_bf16_f32 v137, v197, v198
	v_cvt_pk_bf16_f32 v138, v199, v200
	v_cvt_pk_bf16_f32 v139, v201, v202
	v_cvt_pk_bf16_f32 v140, v203, v204
	v_cvt_pk_bf16_f32 v141, v205, v206
	v_cvt_pk_bf16_f32 v142, v207, v208
	v_cvt_pk_bf16_f32 v143, v209, v194
	s_nop 0
	v_permlane32_swap_b32_e32 v128, v130
	v_permlane32_swap_b32_e32 v129, v131
	v_permlane32_swap_b32_e32 v132, v134
	v_permlane32_swap_b32_e32 v133, v135
	v_permlane32_swap_b32_e32 v136, v138
	v_permlane32_swap_b32_e32 v137, v139
	v_permlane32_swap_b32_e32 v140, v142
	v_permlane32_swap_b32_e32 v141, v143
	s_setprio 0
	v_add_u32_e32 v145, s24, v226
	ds_read_b64_tr_b16 v[146:147], v145 offset:0
	ds_read_b64_tr_b16 v[148:149], v145 offset:0x800
	ds_read_b64_tr_b16 v[150:151], v145 offset:0x1000
	ds_read_b64_tr_b16 v[152:153], v145 offset:0x1800
	ds_read_b64_tr_b16 v[154:155], v145 offset:0x2000
	ds_read_b64_tr_b16 v[156:157], v145 offset:0x2800
	ds_read_b64_tr_b16 v[194:195], v145 offset:0x3000
	ds_read_b64_tr_b16 v[196:197], v145 offset:0x3800
	ds_read_b64_tr_b16 v[198:199], v145 offset:0x200
	ds_read_b64_tr_b16 v[200:201], v145 offset:0xa00
	ds_read_b64_tr_b16 v[202:203], v145 offset:0x1200
	ds_read_b64_tr_b16 v[204:205], v145 offset:0x1a00
	ds_read_b64_tr_b16 v[206:207], v145 offset:0x2200
	ds_read_b64_tr_b16 v[208:209], v145 offset:0x2a00
	ds_read_b64_tr_b16 v[228:229], v145 offset:0x3200
	ds_read_b64_tr_b16 v[230:231], v145 offset:0x3a00
	s_waitcnt lgkmcnt(8)
	s_nop 0
	v_mfma_f32_32x32x16_bf16 v[96:111], v[128:131], v[146:149], v[96:111]
	v_mfma_f32_32x32x16_bf16 v[96:111], v[132:135], v[150:153], v[96:111]
	v_mfma_f32_32x32x16_bf16 v[96:111], v[136:139], v[154:157], v[96:111]
	v_mfma_f32_32x32x16_bf16 v[96:111], v[140:143], v[194:197], v[96:111]
	ds_read_b64_tr_b16 v[146:147], v145 offset:0x400
	ds_read_b64_tr_b16 v[148:149], v145 offset:0xc00
	ds_read_b64_tr_b16 v[150:151], v145 offset:0x1400
	ds_read_b64_tr_b16 v[152:153], v145 offset:0x1c00
	ds_read_b64_tr_b16 v[154:155], v145 offset:0x2400
	ds_read_b64_tr_b16 v[156:157], v145 offset:0x2c00
	ds_read_b64_tr_b16 v[194:195], v145 offset:0x3400
	ds_read_b64_tr_b16 v[196:197], v145 offset:0x3c00
	s_waitcnt lgkmcnt(8)
	v_mfma_f32_32x32x16_bf16 v[112:127], v[128:131], v[198:201], v[112:127]
	v_mfma_f32_32x32x16_bf16 v[112:127], v[132:135], v[202:205], v[112:127]
	v_mfma_f32_32x32x16_bf16 v[112:127], v[136:139], v[206:209], v[112:127]
	v_mfma_f32_32x32x16_bf16 v[112:127], v[140:143], v[228:231], v[112:127]
	ds_read_b64_tr_b16 v[198:199], v145 offset:0x600
	ds_read_b64_tr_b16 v[200:201], v145 offset:0xe00
	ds_read_b64_tr_b16 v[202:203], v145 offset:0x1600
	ds_read_b64_tr_b16 v[204:205], v145 offset:0x1e00
	ds_read_b64_tr_b16 v[206:207], v145 offset:0x2600
	ds_read_b64_tr_b16 v[208:209], v145 offset:0x2e00
	ds_read_b64_tr_b16 v[228:229], v145 offset:0x3600
	ds_read_b64_tr_b16 v[230:231], v145 offset:0x3e00
	s_waitcnt lgkmcnt(8)
; #define SBAR() __builtin_amdgcn_sched_barrier(0)
; #define PV_LOAD(S, DD) do { S[0] = tr_read<v_off8(DD, 0, 0)>(vb); S[1] = tr_read<v_off8(DD, 0, 1)>(vb); S[2] = tr_read<v_off8(DD, 1, 0)>(vb); S[3] = tr_read<v_off8(DD, 1, 1)>(vb); \
;     S[4] = tr_read<v_off8(DD, 2, 0)>(vb); S[5] = tr_read<v_off8(DD, 2, 1)>(vb); S[6] = tr_read<v_off8(DD, 3, 0)>(vb); S[7] = tr_read<v_off8(DD, 3, 1)>(vb); } while (0)
; #define PV_MMA(OD, S) do { OD = __builtin_amdgcn_mfma_f32_32x32x16_bf16(pa0, PV_PK(S[0], S[1]), OD, 0, 0, 0); OD = __builtin_amdgcn_mfma_f32_32x32x16_bf16(pa1, PV_PK(S[2], S[3]), OD, 0, 0, 0); \
;     OD = __builtin_amdgcn_mfma_f32_32x32x16_bf16(pa2, PV_PK(S[4], S[5]), OD, 0, 0, 0); OD = __builtin_amdgcn_mfma_f32_32x32x16_bf16(pa3, PV_PK(S[6], S[7]), OD, 0, 0, 0); } while (0)
; #define PV_W8() do { asm volatile("s_waitcnt lgkmcnt(8)" ::: "memory"); SBAR(); } while (0)
; #define PV_W0() do { asm volatile("s_waitcnt lgkmcnt(0)" ::: "memory"); SBAR(); } while (0)
; #define STEP_SYNC() do { asm volatile("s_waitcnt vmcnt(0) lgkmcnt(0)" ::: "memory"); __builtin_amdgcn_s_barrier(); asm volatile("" ::: "memory"); } while (0)
; #define ROT() do { bprev = bcur; bcur = bnext; bnext = (bnext + BUF_BYTES == NBUF * BUF_BYTES) ? 0 : bnext + BUF_BYTES; } while (0)
; __device__ __forceinline__ void pv8(f32x16* o, int vb, bf16x8 pa0, bf16x8 pa1, bf16x8 pa2, bf16x8 pa3) {
;     ...
;   PV_LOAD(A, 2); PV_W8(); PV_MMA(o[1], B); SBAR();
;   PV_LOAD(B, 3); PV_W8(); PV_MMA(o[2], A); SBAR();
;   PV_LOAD(A, 4); PV_W8(); PV_MMA(o[3], B); SBAR();
;   PV_LOAD(B, 5); PV_W8(); PV_MMA(o[4], A); SBAR();
;   PV_LOAD(A, 6); PV_W8(); PV_MMA(o[5], B); SBAR();
;   PV_LOAD(B, 7); PV_W8(); PV_MMA(o[6], A); SBAR();
;   PV_W0(); PV_MMA(o[7], B);
; __device__ __forceinline__ void attn_pass(const bf16_t* __restrict__ Qb, const bf16_t* __restrict__ Kh, const bf16_t* __restrict__ Vh,
;                                           float* Ob, int mode, float lam, int qpos0, int seq, char* lds, const int wv, bf16_t* OBh) {
;     ...
;       __builtin_amdgcn_s_setprio(0);
;       STEP_SYNC();
;       ROT();
	s_setprio 1
	v_mfma_f32_32x32x16_bf16 v[80:95], v[128:131], v[146:149], v[80:95]
	v_mfma_f32_32x32x16_bf16 v[80:95], v[132:135], v[150:153], v[80:95]
	v_mfma_f32_32x32x16_bf16 v[80:95], v[136:139], v[154:157], v[80:95]
	v_mfma_f32_32x32x16_bf16 v[80:95], v[140:143], v[194:197], v[80:95]
	ds_read_b64_tr_b16 v[146:147], v145 offset:0x4000
	ds_read_b64_tr_b16 v[148:149], v145 offset:0x4800
	ds_read_b64_tr_b16 v[150:151], v145 offset:0x5000
	ds_read_b64_tr_b16 v[152:153], v145 offset:0x5800
	ds_read_b64_tr_b16 v[154:155], v145 offset:0x6000
	ds_read_b64_tr_b16 v[156:157], v145 offset:0x6800
	ds_read_b64_tr_b16 v[194:195], v145 offset:0x7000
	ds_read_b64_tr_b16 v[196:197], v145 offset:0x7800
	s_waitcnt lgkmcnt(8)
	v_mfma_f32_32x32x16_bf16 v[64:79], v[128:131], v[198:201], v[64:79]
	v_mfma_f32_32x32x16_bf16 v[64:79], v[132:135], v[202:205], v[64:79]
	v_mfma_f32_32x32x16_bf16 v[64:79], v[136:139], v[206:209], v[64:79]
	v_mfma_f32_32x32x16_bf16 v[64:79], v[140:143], v[228:231], v[64:79]
	ds_read_b64_tr_b16 v[198:199], v145 offset:0x4200
	ds_read_b64_tr_b16 v[200:201], v145 offset:0x4a00
	ds_read_b64_tr_b16 v[202:203], v145 offset:0x5200
	ds_read_b64_tr_b16 v[204:205], v145 offset:0x5a00
	ds_read_b64_tr_b16 v[206:207], v145 offset:0x6200
	ds_read_b64_tr_b16 v[208:209], v145 offset:0x6a00
	ds_read_b64_tr_b16 v[228:229], v145 offset:0x7200
	ds_read_b64_tr_b16 v[230:231], v145 offset:0x7a00
	s_waitcnt lgkmcnt(8)
	v_mfma_f32_32x32x16_bf16 v[48:63], v[128:131], v[146:149], v[48:63]
	v_mfma_f32_32x32x16_bf16 v[48:63], v[132:135], v[150:153], v[48:63]
	v_mfma_f32_32x32x16_bf16 v[48:63], v[136:139], v[154:157], v[48:63]
	v_mfma_f32_32x32x16_bf16 v[48:63], v[140:143], v[194:197], v[48:63]
	ds_read_b64_tr_b16 v[146:147], v145 offset:0x4400
	ds_read_b64_tr_b16 v[148:149], v145 offset:0x4c00
	ds_read_b64_tr_b16 v[150:151], v145 offset:0x5400
	ds_read_b64_tr_b16 v[152:153], v145 offset:0x5c00
	ds_read_b64_tr_b16 v[154:155], v145 offset:0x6400
	ds_read_b64_tr_b16 v[156:157], v145 offset:0x6c00
	ds_read_b64_tr_b16 v[194:195], v145 offset:0x7400
	ds_read_b64_tr_b16 v[196:197], v145 offset:0x7c00
	s_waitcnt lgkmcnt(8)
	v_mfma_f32_32x32x16_bf16 v[32:47], v[128:131], v[198:201], v[32:47]
	v_mfma_f32_32x32x16_bf16 v[32:47], v[132:135], v[202:205], v[32:47]
	v_mfma_f32_32x32x16_bf16 v[32:47], v[136:139], v[206:209], v[32:47]
	v_mfma_f32_32x32x16_bf16 v[32:47], v[140:143], v[228:231], v[32:47]
	ds_read_b64_tr_b16 v[198:199], v145 offset:0x4600
	ds_read_b64_tr_b16 v[200:201], v145 offset:0x4e00
	ds_read_b64_tr_b16 v[202:203], v145 offset:0x5600
	ds_read_b64_tr_b16 v[204:205], v145 offset:0x5e00
	ds_read_b64_tr_b16 v[206:207], v145 offset:0x6600
	ds_read_b64_tr_b16 v[208:209], v145 offset:0x6e00
	ds_read_b64_tr_b16 v[228:229], v145 offset:0x7600
	ds_read_b64_tr_b16 v[230:231], v145 offset:0x7e00
	s_waitcnt lgkmcnt(8)
	v_mfma_f32_32x32x16_bf16 v[16:31], v[128:131], v[146:149], v[16:31]
	v_mfma_f32_32x32x16_bf16 v[16:31], v[132:135], v[150:153], v[16:31]
	v_mfma_f32_32x32x16_bf16 v[16:31], v[136:139], v[154:157], v[16:31]
	v_mfma_f32_32x32x16_bf16 v[16:31], v[140:143], v[194:197], v[16:31]
	s_waitcnt lgkmcnt(0)
	v_mfma_f32_32x32x16_bf16 v[0:15], v[128:131], v[198:201], v[0:15]
	v_mfma_f32_32x32x16_bf16 v[0:15], v[132:135], v[202:205], v[0:15]
	v_mfma_f32_32x32x16_bf16 v[0:15], v[136:139], v[206:209], v[0:15]
	v_mfma_f32_32x32x16_bf16 v[0:15], v[140:143], v[228:231], v[0:15]
	s_setprio 0
	s_add_i32 s8, s19, 0xc000
	s_cmp_lg_u32 s8, 0x24000
	s_cselect_b32 s8, s8, 0
	s_addk_i32 s2, 0x100
	s_waitcnt vmcnt(0) lgkmcnt(0)
	s_barrier
	s_add_u32 s16, s16, 0xc0000
	s_addc_u32 s17, s17, 0
	s_add_i32 s1, s1, 64
	s_cmp_eq_u32 s2, 0
	s_cbranch_scc0 .LBB0_126
